# adds: LDS fragment base addresses formed once per phase; first mixer ticket = block index; prologue gain vector loaded once outside the row loop
# speedup vs baseline: 1.0092x; 1.0092x over previous
; #define PG8_WAIT_V(n) asm volatile("s_waitcnt vmcnt(" #n ")" ::: "memory")
; #define PG8_BAR __builtin_amdgcn_s_barrier()
; template <class Epi, class Sched, bool ALIGN_EPI = false, bool SP2 = false>
; __device__ __forceinline__ void gemm_phase(PG8_LAS unsigned char* lds, const Gemm g, const Sched& S, const Epi& E, const int tid_in) {
;     ...
;     for (int i = 0; i < 2; ++i) { int R, C; stage_rc(tid * 16 + i * 8192, R, C); const int Rb = Epi::PERM ? ((R & ~31) + perm32(R & 31)) : R;
;         voffA[i] = (unsigned)(R * K + C) * 2u; voffB[i] = (unsigned)(Rb * K + C) * 2u; }
;     const size_t kstep = (size_t)(BK * 2);
;     const size_t hstep = (size_t)HALF * K * 2;
;     const size_t tstep = 2 * hstep;
;     const unsigned ldsw = (unsigned)wid * 1024u;
;     const int aoff = lds_byte(wr * 64 + fr, fq * 8), boff = lds_byte(wc * 32 + fr, fq * 8);
;     ...
;     Unit cur, nxt; int ui = 0;
;     if (!S.next(0, cur)) return;
;     f32x4 acc[2][2][4][2];
; #pragma unroll
;     for (int a = 0; a < 2; ++a)
; #pragma unroll
;         for (int b = 0; b < 2; ++b)
; #pragma unroll
;             for (int m = 0; m < 4; ++m)
; #pragma unroll
;                 for (int n = 0; n < 2; ++n) acc[a][b][m][n] = (f32x4){0.f, 0.f, 0.f, 0.f};
;     bf16x8 At[4][2], B0[2][2], B1[2][2];
;     const char* cA = (const char*)g.A + (size_t)cur.pm * tstep; const char* cB = (const char*)g.Bt + (size_t)cur.pn * tstep;
;     S.a_ready(cur);
;     if constexpr (SP2) {
;         PG8_STAGE(PG8_SB(0, 0), cB, voffB); PG8_STAGE(PG8_SB(0, 1), cB + hstep, voffB); PG8_STAGE(PG8_SA(0, 0), cA, voffA); PG8_STAGE(PG8_SA(0, 1), cA + hstep, voffA);
;         if (wr == 1) PG8_BAR;
;         PG8_WAIT_V(2); PG8_BAR;
;         PG8_STAGE(PG8_SB(1, 0), cB + kstep, voffB); PG8_STAGE(PG8_SA(1, 0), cA + kstep, voffA); PG8_STAGE(PG8_SB(1, 1), cB + hstep + kstep, voffB);
;         PG8_WAIT_V(6); PG8_BAR;
;     } else {
;         PG8_STAGE(PG8_SB(0, 0), cB, voffB); PG8_STAGE(PG8_SA(0, 0), cA, voffA); PG8_STAGE(PG8_SB(0, 1), cB + hstep, voffB); PG8_STAGE(PG8_SA(0, 1), cA + hstep, voffA);
;         if (wr == 1) PG8_BAR;
;         PG8_WAIT_V(4); PG8_BAR;
;         PG8_STAGE(PG8_SB(1, 0), cB + kstep, voffB); PG8_STAGE(PG8_SA(1, 0), cA + kstep, voffA); PG8_STAGE(PG8_SB(1, 1), cB + hstep + kstep, voffB);
;         PG8_WAIT_V(6); PG8_BAR;
;     }
.LBB0_107:
	s_xor_b64 s[0:1], s[90:91], -1
	s_xor_b64 s[18:19], s[6:7], -1
	v_writelane_b32 v255, s0, 20
	v_lshl_add_u64 v[2:3], v[2:3], 0, s[86:87]
	s_waitcnt vmcnt(2)
	s_barrier
	v_writelane_b32 v255, s1, 21
	s_add_u32 s0, s96, 0xa000000
	s_addc_u32 s1, s97, 0
	s_add_i32 m0, s60, 0x18000
	s_add_i32 s66, s60, 0x8000
	global_load_lds_dwordx4 v[2:3], off
	v_lshl_add_u64 v[2:3], v[4:5], 0, s[86:87]
	s_add_i32 m0, s60, 0x1a000
	s_add_i32 s67, s60, 0xa000
	global_load_lds_dwordx4 v[2:3], off
	v_lshl_add_u64 v[2:3], v[10:11], 0, s[86:87]
	s_mov_b32 m0, s66
	v_lshrrev_b32_e32 v19, 1, v236
	global_load_lds_dwordx4 v[2:3], off
	v_lshl_add_u64 v[2:3], v[12:13], 0, s[86:87]
	s_mov_b32 m0, s67
	v_and_b32_e32 v238, 15, v236
	global_load_lds_dwordx4 v[2:3], off
	s_add_i32 m0, s60, 0x1c000
	v_lshl_add_u64 v[2:3], v[6:7], 0, s[86:87]
	global_load_lds_dwordx4 v[2:3], off
	v_lshl_add_u64 v[2:3], v[8:9], 0, s[86:87]
	s_add_i32 m0, s60, 0x1e000
	v_and_b32_e32 v176, 24, v19
	global_load_lds_dwordx4 v[2:3], off
	v_and_b32_e32 v19, 48, v236
	v_lshlrev_b32_e32 v20, 2, v236
	s_and_b32 s64, s5, 3
	s_lshr_b32 s65, s11, 6
	s_lshl_b32 s6, s57, 13
	v_lshl_or_b32 v19, v238, 6, v19
	v_and_b32_e32 v20, 32, v20
	v_bitop3_b32 v21, v19, s6, v20 bitop3:0xde
	s_lshl_b32 s30, s64, 5
	s_lshl_b32 s6, s64, 12
	s_add_i32 s68, s65, -2
	s_cmpk_lt_u32 s4, 0x100
	s_cselect_b64 s[46:47], -1, 0
	s_lshl_b32 s69, s10, 3
	v_cvt_f32_u32_e32 v2, s69
	v_bitop3_b32 v177, s6, v19, v20 bitop3:0xf6
	v_add_u32_e32 v248, 0x10000, v177
	v_add_u32_e32 v249, 0x14000, v177
	v_add_u32_e32 v250, 0x18000, v177
	v_add_u32_e32 v251, 0x1c000, v177
	s_lshl_b32 s6, s5, 4
	s_and_b32 s70, s6, 16
	v_rcp_iflag_f32_e32 v2, v2
	s_sub_i32 s6, 0, s69
	s_ashr_i32 s71, s17, 31
	v_add_u32_e32 v0, v15, v0
	v_mul_f32_e32 v2, 0x4f7ffffe, v2
	v_cvt_u32_f32_e32 v2, v2
	v_add_lshl_u32 v0, v0, v14, 1
	s_waitcnt vmcnt(6)
	v_lshl_or_b32 v237, s57, 6, v238
	v_readfirstlane_b32 s7, v2
	s_mul_i32 s6, s6, s7
	s_mul_hi_u32 s6, s7, s6
	s_add_i32 s72, s7, s6
	s_add_u32 s6, s82, 0x80
	s_addc_u32 s7, 0, 0
	v_lshl_add_u64 v[170:171], s[6:7], 0, v[0:1]
	v_add_u32_e32 v0, v18, v16
	v_add_lshl_u32 v0, v0, v17, 1
	v_mov_b32_e32 v2, 0
	v_or_b32_e32 v178, s30, v176
	s_mov_b32 s35, s83
	s_mov_b32 s73, 0
	v_lshl_add_u64 v[172:173], s[6:7], 0, v[0:1]
	v_add_u32_e32 v179, 0, v21
	v_mov_b32_e32 v3, v2
	v_mov_b32_e32 v4, v2
	v_mov_b32_e32 v5, v2
	v_mov_b32_e32 v6, v2
	v_mov_b32_e32 v7, v2
	v_mov_b32_e32 v8, v2
	v_mov_b32_e32 v9, v2
	v_mov_b32_e32 v18, v2
	v_mov_b32_e32 v19, v2
	v_mov_b32_e32 v20, v2
	v_mov_b32_e32 v21, v2
	v_mov_b32_e32 v22, v2
	v_mov_b32_e32 v23, v2
	v_mov_b32_e32 v24, v2
	v_mov_b32_e32 v25, v2
	v_mov_b32_e32 v34, v2
	v_mov_b32_e32 v35, v2
	v_mov_b32_e32 v36, v2
	v_mov_b32_e32 v37, v2
	v_mov_b32_e32 v38, v2
	v_mov_b32_e32 v39, v2
	v_mov_b32_e32 v40, v2
	v_mov_b32_e32 v41, v2
	v_mov_b32_e32 v50, v2
	v_mov_b32_e32 v51, v2
	v_mov_b32_e32 v52, v2
	v_mov_b32_e32 v53, v2
	v_mov_b32_e32 v54, v2
	v_mov_b32_e32 v55, v2
	v_mov_b32_e32 v56, v2
	v_mov_b32_e32 v57, v2
	v_mov_b32_e32 v10, v2
	v_mov_b32_e32 v11, v2
	v_mov_b32_e32 v12, v2
	v_mov_b32_e32 v13, v2
	v_mov_b32_e32 v14, v2
	v_mov_b32_e32 v15, v2
	v_mov_b32_e32 v16, v2
	v_mov_b32_e32 v17, v2
	v_mov_b32_e32 v26, v2
	v_mov_b32_e32 v27, v2
	v_mov_b32_e32 v28, v2
	v_mov_b32_e32 v29, v2
	v_mov_b32_e32 v30, v2
	v_mov_b32_e32 v31, v2
	v_mov_b32_e32 v32, v2
	v_mov_b32_e32 v33, v2
	v_mov_b32_e32 v42, v2
	v_mov_b32_e32 v43, v2
	v_mov_b32_e32 v44, v2
	v_mov_b32_e32 v45, v2
	v_mov_b32_e32 v46, v2
	v_mov_b32_e32 v47, v2
	v_mov_b32_e32 v48, v2
	v_mov_b32_e32 v49, v2
	v_mov_b32_e32 v58, v2
	v_mov_b32_e32 v59, v2
	v_mov_b32_e32 v60, v2
	v_mov_b32_e32 v61, v2
	v_mov_b32_e32 v62, v2
	v_mov_b32_e32 v63, v2
	v_mov_b32_e32 v64, v2
	v_mov_b32_e32 v65, v2
	v_mov_b32_e32 v66, v2
	v_mov_b32_e32 v67, v2
	v_mov_b32_e32 v68, v2
	v_mov_b32_e32 v69, v2
	v_mov_b32_e32 v70, v2
	v_mov_b32_e32 v71, v2
	v_mov_b32_e32 v72, v2
	v_mov_b32_e32 v73, v2
	v_mov_b32_e32 v82, v2
	v_mov_b32_e32 v83, v2
	v_mov_b32_e32 v84, v2
	v_mov_b32_e32 v85, v2
	v_mov_b32_e32 v86, v2
	v_mov_b32_e32 v87, v2
	v_mov_b32_e32 v88, v2
	v_mov_b32_e32 v89, v2
	v_mov_b32_e32 v98, v2
	v_mov_b32_e32 v99, v2
	v_mov_b32_e32 v100, v2
	v_mov_b32_e32 v101, v2
	v_mov_b32_e32 v102, v2
	v_mov_b32_e32 v103, v2
	v_mov_b32_e32 v104, v2
	v_mov_b32_e32 v105, v2
	v_mov_b32_e32 v114, v2
	v_mov_b32_e32 v115, v2
	v_mov_b32_e32 v116, v2
	v_mov_b32_e32 v117, v2
	v_mov_b32_e32 v118, v2
	v_mov_b32_e32 v119, v2
	v_mov_b32_e32 v120, v2
	v_mov_b32_e32 v121, v2
	v_mov_b32_e32 v74, v2
	v_mov_b32_e32 v75, v2
	v_mov_b32_e32 v76, v2
	v_mov_b32_e32 v77, v2
	v_mov_b32_e32 v78, v2
	v_mov_b32_e32 v79, v2
	v_mov_b32_e32 v80, v2
	v_mov_b32_e32 v81, v2
	v_mov_b32_e32 v90, v2
	v_mov_b32_e32 v91, v2
	v_mov_b32_e32 v92, v2
	v_mov_b32_e32 v93, v2
	v_mov_b32_e32 v94, v2
	v_mov_b32_e32 v95, v2
	v_mov_b32_e32 v96, v2
	v_mov_b32_e32 v97, v2
	v_mov_b32_e32 v106, v2
	v_mov_b32_e32 v107, v2
	v_mov_b32_e32 v108, v2
	v_mov_b32_e32 v109, v2
	v_mov_b32_e32 v110, v2
	v_mov_b32_e32 v111, v2
	v_mov_b32_e32 v112, v2
	v_mov_b32_e32 v113, v2
	v_mov_b32_e32 v122, v2
	v_mov_b32_e32 v123, v2
	v_mov_b32_e32 v124, v2
	v_mov_b32_e32 v125, v2
	v_mov_b32_e32 v126, v2
	v_mov_b32_e32 v127, v2
	v_mov_b32_e32 v128, v2
	v_mov_b32_e32 v129, v2
	s_barrier

; #define PG8_STAGE(bufoff, gbase, voff) do { _Pragma("unroll") for (int _i = 0; _i < 2; ++_i) \
;         __builtin_amdgcn_global_load_lds((const unsigned*)((const char*)(gbase) + (voff)[_i]), (PG8_LAS unsigned*)(lds + (bufoff) + ldsw + _i * 8192), 16, 0, 0); } while (0)
; #define PG8_LDA(dst, b, h) do { _Pragma("unroll") for (int m = 0; m < 4; ++m) _Pragma("unroll") for (int k = 0; k < 2; ++k) dst[m][k] = *(const PG8_LAS bf16x8*)(lds + PG8_SA(b, h) + aoff + m * 2048 + k * 1024); } while (0)
; #define PG8_LDB(dst, b, h) do { _Pragma("unroll") for (int n = 0; n < 2; ++n) _Pragma("unroll") for (int k = 0; k < 2; ++k) dst[n][k] = *(const PG8_LAS bf16x8*)(lds + PG8_SB(b, h) + boff + n * 2048 + k * 1024); } while (0)
; #define PG8_MMA(ai, bj, At, Bt) do { __builtin_amdgcn_s_setprio(1); _Pragma("unroll") for (int m = 0; m < 4; ++m) _Pragma("unroll") for (int n = 0; n < 2; ++n) _Pragma("unroll") for (int k = 0; k < 2; ++k) \
;         acc[ai][bj][m][n] = __builtin_amdgcn_mfma_f32_16x16x32_bf16(Bt[n][k], At[m][k], acc[ai][bj][m][n], 0, 0, 0); __builtin_amdgcn_s_setprio(0); } while (0)
; #define PG8_WAIT_V(n) asm volatile("s_waitcnt vmcnt(" #n ")" ::: "memory")
; #define PG8_WAIT_L(n) asm volatile("s_waitcnt lgkmcnt(" #n ")" ::: "memory")
; #define PG8_BAR __builtin_amdgcn_s_barrier()
; #define PG8_SCHED __builtin_amdgcn_sched_barrier(0)
; template <class Epi, class Sched, bool ALIGN_EPI = false, bool SP2 = false>
; __device__ __forceinline__ void gemm_phase(PG8_LAS unsigned char* lds, const Gemm g, const Sched& S, const Epi& E, const int tid_in) {
;     ...
;             PG8_LDB(B0, 0, 0); PG8_LDB(B1, 0, 1); PG8_SCHED; PG8_LDA(At, 0, 0); PG8_STAGE(PG8_SA(1, 1), a1 + hstep, voffA);
;             PG8_WAIT_V(8); PG8_WAIT_L(0); PG8_BAR; PG8_MMA(0, 0, At, B0); PG8_MMA(0, 1, At, B1); PG8_BAR; PG8_SCHED;
;             PG8_LDA(At, 0, 1); PG8_STAGE(PG8_SB(0, 0), b2, voffB); PG8_STAGE(PG8_SB(0, 1), b2 + hstep, voffB); PG8_STAGE(PG8_SA(0, 0), a2, voffA);
;             PG8_WAIT_V(8); PG8_WAIT_L(0); PG8_BAR; PG8_MMA(1, 0, At, B0); PG8_MMA(1, 1, At, B1); PG8_BAR; PG8_SCHED;
.LBB0_115:
	s_add_i32 s77, s52, 2
	s_add_u32 vcc_lo, s2, s10
	s_addc_u32 s53, s3, s11
	s_add_u32 s44, s50, s10
	s_addc_u32 s45, s51, s11
	s_add_i32 s16, 0, 0x10000
	s_cmp_eq_u32 s68, s52
	s_cselect_b32 s53, s49, s53
	s_cselect_b32 s52, s48, vcc_lo
	s_cselect_b32 vcc_hi, s43, s45
	s_cselect_b32 vcc_lo, s42, s44
	s_add_i32 s17, 0, 0x14000
	ds_read_b128 v[134:137], v248
	ds_read_b128 v[138:141], v248 offset:1024
	ds_read_b128 v[142:145], v248 offset:2048
	ds_read_b128 v[146:149], v248 offset:3072
	ds_read_b128 v[150:153], v249
	ds_read_b128 v[154:157], v249 offset:1024
	ds_read_b128 v[158:161], v249 offset:2048
	ds_read_b128 v[180:183], v249 offset:3072
	s_add_i32 m0, s60, 0xc000
	ds_read_b128 v[184:187], v179
	ds_read_b128 v[188:191], v179 offset:1024
	ds_read_b128 v[192:195], v179 offset:2048
	ds_read_b128 v[196:199], v179 offset:3072
	ds_read_b128 v[200:203], v179 offset:4096
	ds_read_b128 v[204:207], v179 offset:5120
	ds_read_b128 v[208:211], v179 offset:6144
	ds_read_b128 v[212:215], v179 offset:7168
	global_load_lds_dwordx4 v132, s[2:3]
	s_add_i32 m0, s60, 0xe000
	s_nop 0
	global_load_lds_dwordx4 v130, s[2:3]
	s_waitcnt vmcnt(8)
	s_waitcnt lgkmcnt(0)
	s_barrier
	s_setprio 1
	s_waitcnt lgkmcnt(0)
	v_mfma_f32_16x16x32_bf16 v[126:129], v[134:137], v[184:187], v[126:129]
	v_mfma_f32_16x16x32_bf16 v[122:125], v[142:145], v[184:187], v[122:125]
	v_mfma_f32_16x16x32_bf16 v[110:113], v[134:137], v[192:195], v[110:113]
	v_mfma_f32_16x16x32_bf16 v[106:109], v[142:145], v[192:195], v[106:109]
	v_mfma_f32_16x16x32_bf16 v[94:97], v[134:137], v[200:203], v[94:97]
	v_mfma_f32_16x16x32_bf16 v[90:93], v[142:145], v[200:203], v[90:93]
	v_mfma_f32_16x16x32_bf16 v[78:81], v[134:137], v[208:211], v[78:81]
	v_mfma_f32_16x16x32_bf16 v[74:77], v[142:145], v[208:211], v[74:77]
	v_mfma_f32_16x16x32_bf16 v[126:129], v[138:141], v[188:191], v[126:129]
	v_mfma_f32_16x16x32_bf16 v[122:125], v[146:149], v[188:191], v[122:125]
	v_mfma_f32_16x16x32_bf16 v[110:113], v[138:141], v[196:199], v[110:113]
	v_mfma_f32_16x16x32_bf16 v[106:109], v[146:149], v[196:199], v[106:109]
	v_mfma_f32_16x16x32_bf16 v[94:97], v[138:141], v[204:207], v[94:97]
	v_mfma_f32_16x16x32_bf16 v[90:93], v[146:149], v[204:207], v[90:93]
	v_mfma_f32_16x16x32_bf16 v[78:81], v[138:141], v[212:215], v[78:81]
	v_mfma_f32_16x16x32_bf16 v[74:77], v[146:149], v[212:215], v[74:77]
	s_setprio 0
	s_setprio 1
	v_mfma_f32_16x16x32_bf16 v[118:121], v[150:153], v[184:187], v[118:121]
	v_mfma_f32_16x16x32_bf16 v[114:117], v[158:161], v[184:187], v[114:117]
	v_mfma_f32_16x16x32_bf16 v[102:105], v[150:153], v[192:195], v[102:105]
	v_mfma_f32_16x16x32_bf16 v[98:101], v[158:161], v[192:195], v[98:101]
	v_mfma_f32_16x16x32_bf16 v[86:89], v[150:153], v[200:203], v[86:89]
	v_mfma_f32_16x16x32_bf16 v[82:85], v[158:161], v[200:203], v[82:85]
	v_mfma_f32_16x16x32_bf16 v[70:73], v[150:153], v[208:211], v[70:73]
	v_mfma_f32_16x16x32_bf16 v[66:69], v[158:161], v[208:211], v[66:69]
	v_mfma_f32_16x16x32_bf16 v[118:121], v[154:157], v[188:191], v[118:121]
	v_mfma_f32_16x16x32_bf16 v[114:117], v[180:183], v[188:191], v[114:117]
	v_mfma_f32_16x16x32_bf16 v[102:105], v[154:157], v[196:199], v[102:105]
	v_mfma_f32_16x16x32_bf16 v[98:101], v[180:183], v[196:199], v[98:101]
	v_mfma_f32_16x16x32_bf16 v[86:89], v[154:157], v[204:207], v[86:89]
	v_mfma_f32_16x16x32_bf16 v[82:85], v[180:183], v[204:207], v[82:85]
	v_mfma_f32_16x16x32_bf16 v[70:73], v[154:157], v[212:215], v[70:73]
	v_mfma_f32_16x16x32_bf16 v[66:69], v[180:183], v[212:215], v[66:69]
	s_setprio 0
	s_barrier
	s_add_i32 s16, s16, s59
	s_add_u32 s98, vcc_lo, 0x80
	s_addc_u32 s99, vcc_hi, 0
	s_add_u32 s100, s52, 0x80
	s_addc_u32 s101, s53, 0
	s_mov_b32 m0, s16
	ds_read_b128 v[184:187], v179 offset:16384
	ds_read_b128 v[188:191], v179 offset:17408
	ds_read_b128 v[192:195], v179 offset:18432
	ds_read_b128 v[196:199], v179 offset:19456
	ds_read_b128 v[200:203], v179 offset:20480
	ds_read_b128 v[204:207], v179 offset:21504
	ds_read_b128 v[208:211], v179 offset:22528
	ds_read_b128 v[212:215], v179 offset:23552
	global_load_lds_dwordx4 v164, vcc
	s_add_i32 m0, s16, 0x2000
	s_add_i32 s16, s17, s59
	global_load_lds_dwordx4 v168, vcc
	s_add_u32 vcc_lo, vcc_lo, s82
	s_addc_u32 vcc_hi, vcc_hi, 0
	s_mov_b32 m0, s16
	s_nop 0
	global_load_lds_dwordx4 v164, vcc
	s_add_i32 m0, s16, 0x2000
	s_nop 0
	global_load_lds_dwordx4 v168, vcc
	s_mov_b32 m0, s60
	s_nop 0
	global_load_lds_dwordx4 v162, s[52:53]
	s_mov_b32 m0, s61
	s_nop 0
	global_load_lds_dwordx4 v166, s[52:53]
	s_waitcnt vmcnt(8)
	s_waitcnt lgkmcnt(0)
	s_barrier
; #define PG8_STAGE(bufoff, gbase, voff) do { _Pragma("unroll") for (int _i = 0; _i < 2; ++_i) \
;         __builtin_amdgcn_global_load_lds((const unsigned*)((const char*)(gbase) + (voff)[_i]), (PG8_LAS unsigned*)(lds + (bufoff) + ldsw + _i * 8192), 16, 0, 0); } while (0)
; #define PG8_LDA(dst, b, h) do { _Pragma("unroll") for (int m = 0; m < 4; ++m) _Pragma("unroll") for (int k = 0; k < 2; ++k) dst[m][k] = *(const PG8_LAS bf16x8*)(lds + PG8_SA(b, h) + aoff + m * 2048 + k * 1024); } while (0)
; #define PG8_LDB(dst, b, h) do { _Pragma("unroll") for (int n = 0; n < 2; ++n) _Pragma("unroll") for (int k = 0; k < 2; ++k) dst[n][k] = *(const PG8_LAS bf16x8*)(lds + PG8_SB(b, h) + boff + n * 2048 + k * 1024); } while (0)
; #define PG8_MMA(ai, bj, At, Bt) do { __builtin_amdgcn_s_setprio(1); _Pragma("unroll") for (int m = 0; m < 4; ++m) _Pragma("unroll") for (int n = 0; n < 2; ++n) _Pragma("unroll") for (int k = 0; k < 2; ++k) \
;         acc[ai][bj][m][n] = __builtin_amdgcn_mfma_f32_16x16x32_bf16(Bt[n][k], At[m][k], acc[ai][bj][m][n], 0, 0, 0); __builtin_amdgcn_s_setprio(0); } while (0)
; #define PG8_WAIT_V(n) asm volatile("s_waitcnt vmcnt(" #n ")" ::: "memory")
; #define PG8_WAIT_L(n) asm volatile("s_waitcnt lgkmcnt(" #n ")" ::: "memory")
; #define PG8_BAR __builtin_amdgcn_s_barrier()
; #define PG8_SCHED __builtin_amdgcn_sched_barrier(0)
; template <class Epi, class Sched, bool ALIGN_EPI = false, bool SP2 = false>
; __device__ __forceinline__ void gemm_phase(PG8_LAS unsigned char* lds, const Gemm g, const Sched& S, const Epi& E, const int tid_in) {
;     ...
;             PG8_WAIT_V(8); PG8_WAIT_L(0); PG8_BAR; PG8_MMA(1, 0, At, B0); PG8_MMA(1, 1, At, B1); PG8_BAR; PG8_SCHED;
;             PG8_LDB(B0, 1, 0); PG8_LDB(B1, 1, 1); PG8_SCHED; PG8_LDA(At, 1, 0); PG8_STAGE(PG8_SA(0, 1), a2 + hstep, voffA);
;             PG8_WAIT_V(8); PG8_WAIT_L(0); PG8_BAR; PG8_MMA(0, 0, At, B0); PG8_MMA(0, 1, At, B1); PG8_BAR; PG8_SCHED;
	s_setprio 1
	s_waitcnt lgkmcnt(0)
	v_mfma_f32_16x16x32_bf16 v[62:65], v[134:137], v[184:187], v[62:65]
	v_mfma_f32_16x16x32_bf16 v[58:61], v[142:145], v[184:187], v[58:61]
	v_mfma_f32_16x16x32_bf16 v[46:49], v[134:137], v[192:195], v[46:49]
	v_mfma_f32_16x16x32_bf16 v[42:45], v[142:145], v[192:195], v[42:45]
	v_mfma_f32_16x16x32_bf16 v[30:33], v[134:137], v[200:203], v[30:33]
	v_mfma_f32_16x16x32_bf16 v[26:29], v[142:145], v[200:203], v[26:29]
	v_mfma_f32_16x16x32_bf16 v[14:17], v[134:137], v[208:211], v[14:17]
	v_mfma_f32_16x16x32_bf16 v[10:13], v[142:145], v[208:211], v[10:13]
	v_mfma_f32_16x16x32_bf16 v[62:65], v[138:141], v[188:191], v[62:65]
	v_mfma_f32_16x16x32_bf16 v[58:61], v[146:149], v[188:191], v[58:61]
	v_mfma_f32_16x16x32_bf16 v[46:49], v[138:141], v[196:199], v[46:49]
	v_mfma_f32_16x16x32_bf16 v[42:45], v[146:149], v[196:199], v[42:45]
	v_mfma_f32_16x16x32_bf16 v[30:33], v[138:141], v[204:207], v[30:33]
	v_mfma_f32_16x16x32_bf16 v[26:29], v[146:149], v[204:207], v[26:29]
	v_mfma_f32_16x16x32_bf16 v[14:17], v[138:141], v[212:215], v[14:17]
	v_mfma_f32_16x16x32_bf16 v[10:13], v[146:149], v[212:215], v[10:13]
	s_setprio 0
	s_setprio 1
	v_mfma_f32_16x16x32_bf16 v[54:57], v[150:153], v[184:187], v[54:57]
	v_mfma_f32_16x16x32_bf16 v[50:53], v[158:161], v[184:187], v[50:53]
	v_mfma_f32_16x16x32_bf16 v[38:41], v[150:153], v[192:195], v[38:41]
	v_mfma_f32_16x16x32_bf16 v[34:37], v[158:161], v[192:195], v[34:37]
	v_mfma_f32_16x16x32_bf16 v[22:25], v[150:153], v[200:203], v[22:25]
	v_mfma_f32_16x16x32_bf16 v[18:21], v[158:161], v[200:203], v[18:21]
	v_mfma_f32_16x16x32_bf16 v[6:9], v[150:153], v[208:211], v[6:9]
	v_mfma_f32_16x16x32_bf16 v[2:5], v[158:161], v[208:211], v[2:5]
	v_mfma_f32_16x16x32_bf16 v[54:57], v[154:157], v[188:191], v[54:57]
	v_mfma_f32_16x16x32_bf16 v[50:53], v[180:183], v[188:191], v[50:53]
	v_mfma_f32_16x16x32_bf16 v[38:41], v[154:157], v[196:199], v[38:41]
	v_mfma_f32_16x16x32_bf16 v[34:37], v[180:183], v[196:199], v[34:37]
	v_mfma_f32_16x16x32_bf16 v[22:25], v[154:157], v[204:207], v[22:25]
	v_mfma_f32_16x16x32_bf16 v[18:21], v[180:183], v[204:207], v[18:21]
	v_mfma_f32_16x16x32_bf16 v[6:9], v[154:157], v[212:215], v[6:9]
	v_mfma_f32_16x16x32_bf16 v[2:5], v[180:183], v[212:215], v[2:5]
	s_setprio 0
	s_barrier
	s_add_i32 s16, 0, 0x18000
	s_add_i32 s17, 0, 0x1c000
	ds_read_b128 v[134:137], v250
	ds_read_b128 v[138:141], v250 offset:1024
	ds_read_b128 v[142:145], v250 offset:2048
	ds_read_b128 v[146:149], v250 offset:3072
	ds_read_b128 v[150:153], v251
	ds_read_b128 v[154:157], v251 offset:1024
	ds_read_b128 v[158:161], v251 offset:2048
	ds_read_b128 v[180:183], v251 offset:3072
	s_add_u32 s52, s52, s82
	s_addc_u32 s53, s53, 0
	s_mov_b32 m0, s62
	ds_read_b128 v[184:187], v179 offset:32768
	ds_read_b128 v[188:191], v179 offset:33792
	ds_read_b128 v[192:195], v179 offset:34816
	ds_read_b128 v[196:199], v179 offset:35840
	ds_read_b128 v[200:203], v179 offset:36864
	ds_read_b128 v[204:207], v179 offset:37888
	ds_read_b128 v[208:211], v179 offset:38912
	ds_read_b128 v[212:215], v179 offset:39936
	global_load_lds_dwordx4 v162, s[52:53]
	s_mov_b32 m0, s63
	s_nop 0
	global_load_lds_dwordx4 v166, s[52:53]
	s_waitcnt vmcnt(8)
	s_waitcnt lgkmcnt(0)
	s_barrier
	s_setprio 1
	s_waitcnt lgkmcnt(0)
	v_mfma_f32_16x16x32_bf16 v[126:129], v[134:137], v[184:187], v[126:129]
	v_mfma_f32_16x16x32_bf16 v[122:125], v[142:145], v[184:187], v[122:125]
	v_mfma_f32_16x16x32_bf16 v[110:113], v[134:137], v[192:195], v[110:113]
	v_mfma_f32_16x16x32_bf16 v[106:109], v[142:145], v[192:195], v[106:109]
	v_mfma_f32_16x16x32_bf16 v[94:97], v[134:137], v[200:203], v[94:97]
	v_mfma_f32_16x16x32_bf16 v[90:93], v[142:145], v[200:203], v[90:93]
	v_mfma_f32_16x16x32_bf16 v[78:81], v[134:137], v[208:211], v[78:81]
	v_mfma_f32_16x16x32_bf16 v[74:77], v[142:145], v[208:211], v[74:77]
	v_mfma_f32_16x16x32_bf16 v[126:129], v[138:141], v[188:191], v[126:129]
	v_mfma_f32_16x16x32_bf16 v[122:125], v[146:149], v[188:191], v[122:125]
	v_mfma_f32_16x16x32_bf16 v[110:113], v[138:141], v[196:199], v[110:113]
	v_mfma_f32_16x16x32_bf16 v[106:109], v[146:149], v[196:199], v[106:109]
	v_mfma_f32_16x16x32_bf16 v[94:97], v[138:141], v[204:207], v[94:97]
	v_mfma_f32_16x16x32_bf16 v[90:93], v[146:149], v[204:207], v[90:93]
	v_mfma_f32_16x16x32_bf16 v[78:81], v[138:141], v[212:215], v[78:81]
	v_mfma_f32_16x16x32_bf16 v[74:77], v[146:149], v[212:215], v[74:77]
	s_setprio 0
	s_setprio 1
	v_mfma_f32_16x16x32_bf16 v[118:121], v[150:153], v[184:187], v[118:121]
	v_mfma_f32_16x16x32_bf16 v[114:117], v[158:161], v[184:187], v[114:117]
	v_mfma_f32_16x16x32_bf16 v[102:105], v[150:153], v[192:195], v[102:105]
	v_mfma_f32_16x16x32_bf16 v[98:101], v[158:161], v[192:195], v[98:101]
	v_mfma_f32_16x16x32_bf16 v[86:89], v[150:153], v[200:203], v[86:89]
	v_mfma_f32_16x16x32_bf16 v[82:85], v[158:161], v[200:203], v[82:85]
	v_mfma_f32_16x16x32_bf16 v[70:73], v[150:153], v[208:211], v[70:73]
	v_mfma_f32_16x16x32_bf16 v[66:69], v[158:161], v[208:211], v[66:69]
	v_mfma_f32_16x16x32_bf16 v[118:121], v[154:157], v[188:191], v[118:121]
	v_mfma_f32_16x16x32_bf16 v[114:117], v[180:183], v[188:191], v[114:117]
	v_mfma_f32_16x16x32_bf16 v[102:105], v[154:157], v[196:199], v[102:105]
	v_mfma_f32_16x16x32_bf16 v[98:101], v[180:183], v[196:199], v[98:101]
	v_mfma_f32_16x16x32_bf16 v[86:89], v[154:157], v[204:207], v[86:89]
	v_mfma_f32_16x16x32_bf16 v[82:85], v[180:183], v[204:207], v[82:85]
	v_mfma_f32_16x16x32_bf16 v[70:73], v[154:157], v[212:215], v[70:73]
	v_mfma_f32_16x16x32_bf16 v[66:69], v[180:183], v[212:215], v[66:69]
	s_setprio 0
	s_barrier
; #define PG8_STAGE(bufoff, gbase, voff) do { _Pragma("unroll") for (int _i = 0; _i < 2; ++_i) \
;         __builtin_amdgcn_global_load_lds((const unsigned*)((const char*)(gbase) + (voff)[_i]), (PG8_LAS unsigned*)(lds + (bufoff) + ldsw + _i * 8192), 16, 0, 0); } while (0)
; #define PG8_LDA(dst, b, h) do { _Pragma("unroll") for (int m = 0; m < 4; ++m) _Pragma("unroll") for (int k = 0; k < 2; ++k) dst[m][k] = *(const PG8_LAS bf16x8*)(lds + PG8_SA(b, h) + aoff + m * 2048 + k * 1024); } while (0)
; #define PG8_MMA(ai, bj, At, Bt) do { __builtin_amdgcn_s_setprio(1); _Pragma("unroll") for (int m = 0; m < 4; ++m) _Pragma("unroll") for (int n = 0; n < 2; ++n) _Pragma("unroll") for (int k = 0; k < 2; ++k) \
;         acc[ai][bj][m][n] = __builtin_amdgcn_mfma_f32_16x16x32_bf16(Bt[n][k], At[m][k], acc[ai][bj][m][n], 0, 0, 0); __builtin_amdgcn_s_setprio(0); } while (0)
; #define PG8_WAIT_V(n) asm volatile("s_waitcnt vmcnt(" #n ")" ::: "memory")
; #define PG8_WAIT_L(n) asm volatile("s_waitcnt lgkmcnt(" #n ")" ::: "memory")
; #define PG8_BAR __builtin_amdgcn_s_barrier()
; #define PG8_SCHED __builtin_amdgcn_sched_barrier(0)
; template <class Epi, class Sched, bool ALIGN_EPI = false, bool SP2 = false>
; __device__ __forceinline__ void gemm_phase(PG8_LAS unsigned char* lds, const Gemm g, const Sched& S, const Epi& E, const int tid_in) {
;     ...
;         for (int t = 0; t < nt; t += 2) {
;             const bool last = (t == nt - 2);
;             const char* a1 = cA + (size_t)(t + 1) * kstep;
;     ...
;             PG8_LDA(At, 1, 1); PG8_STAGE(PG8_SB(1, 0), b3, voffB); PG8_STAGE(PG8_SB(1, 1), b3 + hstep, voffB); PG8_STAGE(PG8_SA(1, 0), a3, voffA);
;             PG8_WAIT_V(8); PG8_WAIT_L(0); PG8_BAR; PG8_MMA(1, 0, At, B0); PG8_MMA(1, 1, At, B1); PG8_BAR; PG8_SCHED;
	s_add_i32 s16, s16, s59
	s_mov_b32 m0, s16
	ds_read_b128 v[184:187], v179 offset:49152
	ds_read_b128 v[188:191], v179 offset:50176
	ds_read_b128 v[192:195], v179 offset:51200
	ds_read_b128 v[196:199], v179 offset:52224
	ds_read_b128 v[200:203], v179 offset:53248
	ds_read_b128 v[204:207], v179 offset:54272
	ds_read_b128 v[208:211], v179 offset:55296
	ds_read_b128 v[212:215], v179 offset:56320
	global_load_lds_dwordx4 v164, s[98:99]
	s_add_i32 m0, s16, 0x2000
	s_add_i32 s16, s17, s59
	global_load_lds_dwordx4 v168, s[98:99]
	s_add_u32 vcc_lo, vcc_lo, 0x80
	s_addc_u32 vcc_hi, vcc_hi, 0
	s_mov_b32 m0, s16
	s_nop 0
	global_load_lds_dwordx4 v164, vcc
	s_add_i32 m0, s16, 0x2000
	s_nop 0
	global_load_lds_dwordx4 v168, vcc
	s_mov_b32 m0, s66
	s_nop 0
	global_load_lds_dwordx4 v162, s[100:101]
	s_mov_b32 m0, s67
	s_nop 0
	global_load_lds_dwordx4 v166, s[100:101]
	s_waitcnt vmcnt(8)
	s_waitcnt lgkmcnt(0)
	s_barrier
	s_setprio 1
	s_waitcnt lgkmcnt(0)
	v_mfma_f32_16x16x32_bf16 v[62:65], v[134:137], v[184:187], v[62:65]
	v_mfma_f32_16x16x32_bf16 v[58:61], v[142:145], v[184:187], v[58:61]
	v_mfma_f32_16x16x32_bf16 v[46:49], v[134:137], v[192:195], v[46:49]
	v_mfma_f32_16x16x32_bf16 v[42:45], v[142:145], v[192:195], v[42:45]
	v_mfma_f32_16x16x32_bf16 v[30:33], v[134:137], v[200:203], v[30:33]
	v_mfma_f32_16x16x32_bf16 v[26:29], v[142:145], v[200:203], v[26:29]
	v_mfma_f32_16x16x32_bf16 v[14:17], v[134:137], v[208:211], v[14:17]
	v_mfma_f32_16x16x32_bf16 v[10:13], v[142:145], v[208:211], v[10:13]
	v_mfma_f32_16x16x32_bf16 v[62:65], v[138:141], v[188:191], v[62:65]
	v_mfma_f32_16x16x32_bf16 v[58:61], v[146:149], v[188:191], v[58:61]
	v_mfma_f32_16x16x32_bf16 v[46:49], v[138:141], v[196:199], v[46:49]
	v_mfma_f32_16x16x32_bf16 v[42:45], v[146:149], v[196:199], v[42:45]
	v_mfma_f32_16x16x32_bf16 v[30:33], v[138:141], v[204:207], v[30:33]
	v_mfma_f32_16x16x32_bf16 v[26:29], v[146:149], v[204:207], v[26:29]
	v_mfma_f32_16x16x32_bf16 v[14:17], v[138:141], v[212:215], v[14:17]
	v_mfma_f32_16x16x32_bf16 v[10:13], v[146:149], v[212:215], v[10:13]
	s_setprio 0
	s_setprio 1
	v_mfma_f32_16x16x32_bf16 v[54:57], v[150:153], v[184:187], v[54:57]
	v_mfma_f32_16x16x32_bf16 v[50:53], v[158:161], v[184:187], v[50:53]
	v_mfma_f32_16x16x32_bf16 v[38:41], v[150:153], v[192:195], v[38:41]
	v_mfma_f32_16x16x32_bf16 v[34:37], v[158:161], v[192:195], v[34:37]
	v_mfma_f32_16x16x32_bf16 v[22:25], v[150:153], v[200:203], v[22:25]
	v_mfma_f32_16x16x32_bf16 v[18:21], v[158:161], v[200:203], v[18:21]
	v_mfma_f32_16x16x32_bf16 v[6:9], v[150:153], v[208:211], v[6:9]
	v_mfma_f32_16x16x32_bf16 v[2:5], v[158:161], v[208:211], v[2:5]
	v_mfma_f32_16x16x32_bf16 v[54:57], v[154:157], v[188:191], v[54:57]
	v_mfma_f32_16x16x32_bf16 v[50:53], v[180:183], v[188:191], v[50:53]
	v_mfma_f32_16x16x32_bf16 v[38:41], v[154:157], v[196:199], v[38:41]
	v_mfma_f32_16x16x32_bf16 v[34:37], v[180:183], v[196:199], v[34:37]
	v_mfma_f32_16x16x32_bf16 v[22:25], v[154:157], v[204:207], v[22:25]
	v_mfma_f32_16x16x32_bf16 v[18:21], v[180:183], v[204:207], v[18:21]
	v_mfma_f32_16x16x32_bf16 v[6:9], v[154:157], v[212:215], v[6:9]
	v_mfma_f32_16x16x32_bf16 v[2:5], v[180:183], v[212:215], v[2:5]
	s_setprio 0
	s_barrier
	s_add_u32 s10, s10, 0x100
	s_addc_u32 s11, s11, 0
	v_lshl_add_u64 v[132:133], v[132:133], 0, s[88:89]
	v_lshl_add_u64 v[130:131], v[130:131], 0, s[88:89]
	s_cmp_ge_u32 s77, s65
	s_mov_b32 s52, s77
	s_cbranch_scc0 .LBB0_115
	s_and_b64 vcc, exec, s[46:47]
	s_cbranch_vccz .LBB0_118
	s_barrier

; #define LAS __attribute__((address_space(3)))
; __global__ void __launch_bounds__(NTHREADS, 2) fwd_megakernel(Params p_) {
;     ...
;             unsigned* qctr = (unsigned*)(ws + WS_CTL + CTL_Q) + 64 * L;
;             volatile LAS unsigned* qslot = (volatile LAS unsigned*)(lds + LDS_MISC + 16);
;             const int total = even ? 1024 : 640;
;             for (;;) {
;                 if (tid == 0) *qslot = __hip_atomic_fetch_add(qctr, 1u, __ATOMIC_RELAXED, __HIP_MEMORY_SCOPE_AGENT);
;                 __syncthreads();
;                 const int idx = __builtin_amdgcn_readfirstlane((int)*qslot);
.LBB0_317:
	s_and_b64 vcc, exec, s[0:1]
	s_cbranch_vccz .LBB0_494
	s_lshl_b32 s2, s13, 6
	s_ashr_i32 s3, s2, 31
	s_ashr_i32 s0, s13, 1
	s_lshl_b64 s[2:3], s[2:3], 2
	s_add_u32 s1, s96, s2
	s_addc_u32 s2, s97, s3
	s_add_u32 s4, s1, 0x1590c000
	s_addc_u32 s5, s2, 0
	s_and_b64 s[2:3], s[28:29], exec
	s_movk_i32 s1, 0x280
	v_writelane_b32 v255, s4, 18
	s_cselect_b32 s13, 0x400, s1
	s_lshl_b32 s2, s0, 9
	v_writelane_b32 v255, s5, 19
	s_ashr_i32 s3, s2, 31
	v_writelane_b32 v255, s2, 20
	s_ashr_i32 s1, s0, 31
	v_cmp_eq_u32_e64 s[18:19], 0, v236
	v_writelane_b32 v255, s3, 21
	s_lshl_b64 s[2:3], s[0:1], 18
	v_writelane_b32 v255, s2, 22
	s_mul_hi_i32 s1, s0, 0xf800
	s_mul_i32 s0, s0, 0xf800
	v_writelane_b32 v255, s3, 23
	v_writelane_b32 v255, s1, 24
	v_writelane_b32 v255, s0, 25
	s_add_u32 s0, s96, 0xc100400
	v_writelane_b32 v255, s0, 26
	s_addc_u32 s0, s97, 0
	v_writelane_b32 v255, s0, 27
	s_add_u32 s0, s96, 0xc1f0400
	s_addc_u32 s1, s97, 0
	v_writelane_b32 v255, s0, 28
	s_nop 1
	v_writelane_b32 v255, s1, 29
	v_writelane_b32 v255, s13, 30
	v_writelane_b32 v255, s18, 32
	s_nop 1
	v_writelane_b32 v255, s19, 33
	v_writelane_b32 v255, s84, 34
	s_nop 1
	v_writelane_b32 v255, s85, 35
	s_and_saveexec_b64 s[0:1], s[18:19]
	s_cbranch_execz .LBB0_326
	v_readlane_b32 s2, v255, 11
	v_mov_b32_e32 v2, s76
	s_nop 1
	v_mov_b32_e32 v0, s2
	ds_write_b32 v2, v0
	s_branch .LBB0_326

; __global__ void __launch_bounds__(NTHREADS, 2) fwd_megakernel(Params p_) {
;     ...
;                 if (tid == 0) *qslot = __hip_atomic_fetch_add(qctr, 1u, __ATOMIC_RELAXED, __HIP_MEMORY_SCOPE_AGENT);
;                 __syncthreads();
;                 const int idx = __builtin_amdgcn_readfirstlane((int)*qslot);
.LBB0_325:
	s_or_b64 exec, exec, s[2:3]
	s_waitcnt vmcnt(0)
	v_readfirstlane_b32 s2, v2
	v_readlane_b32 s3, v255, 10
	v_mov_b32_e32 v2, s76
	s_add_i32 s2, s2, s3
	v_add_u32_e32 v0, s2, v0
	ds_write_b32 v2, v0

; __device__ __forceinline__ unsigned cvtpk(float lo, float hi) { f32x2_t v = {lo, hi}; bf16x2_t b = __builtin_convertvector(v, bf16x2_t); return __builtin_bit_cast(unsigned, b); }
; __device__ __forceinline__ float bflo(unsigned u) { return __uint_as_float(u << 16); }
; __device__ __forceinline__ float bfhi(unsigned u) { return __uint_as_float(u & 0xffff0000u); }
; __device__ __forceinline__ void row_pass(const float* xsrc, float* xdst, const bf16* F, float coef, const float* g_post, const float* g_pre, bf16* XN, int gw, int NGW, int lane) {
;     for (int m = gw; m < M; m += NGW) {
;         const f32x4* xr = (const f32x4*)(xsrc + (size_t)m * D) + lane;
;         f32x4 v[4];
; #pragma unroll
;         for (int j = 0; j < 4; ++j) v[j] = xr[64 * j];
;         if (F) {
;             const u32x2* fr = (const u32x2*)(F + (size_t)m * D) + lane; f32x4 f[4]; float ss = 0.f;
; #pragma unroll
;             for (int j = 0; j < 4; ++j) { const u32x2 w = fr[64 * j]; f[j] = (f32x4){bflo(w.x), bfhi(w.x), bflo(w.y), bfhi(w.y)}; ss += (f[j].x * f[j].x + f[j].y * f[j].y) + (f[j].z * f[j].z + f[j].w * f[j].w); }
;             const float rs = coef / sqrtf(wave_sum(ss, lane) * (1.f / D) + 1e-6f);
; #pragma unroll
;             for (int j = 0; j < 4; ++j) { const f32x4 g = ((const f32x4*)g_post)[lane + 64 * j]; v[j] = v[j] + f[j] * g * rs; }
;         }
;         u32x2* xo = (u32x2*)((bf16*)xdst + (size_t)m * D) + lane;
; #pragma unroll
;         for (int j = 0; j < 4; ++j) { u32x2 w; w.x = cvtpk(v[j].x, v[j].y); w.y = cvtpk(v[j].z, v[j].w); xo[64 * j] = w; }
;         if (XN) {
;             float ss = 0.f;
; #pragma unroll
;             for (int j = 0; j < 4; ++j) ss += (v[j].x * v[j].x + v[j].y * v[j].y) + (v[j].z * v[j].z + v[j].w * v[j].w);
;             const float rs = 1.0f / sqrtf(wave_sum(ss, lane) * (1.f / D) + 1e-6f);
;             u32x2* o8 = (u32x2*)(XN + (size_t)m * D) + lane;
; #pragma unroll
;             for (int j = 0; j < 4; ++j) { const f32x4 g = ((const f32x4*)g_pre)[lane + 64 * j]; const f32x4 y = v[j] * g * rs; u32x2 w; w.x = cvtpk(y.x, y.y); w.y = cvtpk(y.z, y.w); o8[64 * j] = w; }
;         }
.LBB0_516:
	s_or_b64 exec, exec, s[2:3]
	s_cmpk_gt_i32 s10, 0x3fff
	s_cbranch_scc1 .LBB0_7
	s_load_dwordx4 s[4:7], s[78:79], 0x0
	v_lshlrev_b32_e32 v0, 2, v3
	v_xor_b32_e32 v12, 4, v0
	v_xor_b32_e32 v13, 8, v0
	v_xor_b32_e32 v14, 16, v0
	v_xor_b32_e32 v15, 32, v0
	v_xor_b32_e32 v16, 64, v0
	v_xor_b32_e32 v17, 0x80, v0
	v_lshlrev_b32_e32 v0, 4, v3
	s_ashr_i32 s2, s11, 31
	s_ashr_i32 s3, s1, 31
	s_waitcnt lgkmcnt(0)
	v_lshl_add_u64 v[6:7], s[6:7], 0, v[0:1]
	s_add_u32 s6, s11, s1
	s_addc_u32 s7, s2, s3
	s_lshl_b64 s[2:3], s[6:7], 11
	s_add_u32 s2, s96, s2
	v_mov_b32_e32 v3, v1
	s_addc_u32 s3, s97, s3
	v_lshl_add_u64 v[2:3], s[2:3], 0, v[2:3]
	s_mov_b64 s[2:3], 0x11900600
	s_ashr_i32 s1, s0, 31
	v_lshl_add_u64 v[8:9], v[2:3], 0, s[2:3]
	s_lshl_b64 s[2:3], s[0:1], 11
	s_lshl_b64 s[6:7], s[6:7], 12
	s_add_u32 s4, s4, s6
	s_addc_u32 s5, s5, s7
	v_lshl_add_u64 v[2:3], s[4:5], 0, v[0:1]
	s_mov_b64 s[4:5], 0xc00
	v_lshl_add_u64 v[10:11], v[2:3], 0, s[4:5]
	s_lshl_b64 s[4:5], s[0:1], 12
	global_load_dwordx4 v[60:63], v[6:7], off
	global_load_dwordx4 v[64:67], v[6:7], off offset:1024
	global_load_dwordx4 v[68:71], v[6:7], off offset:2048
	global_load_dwordx4 v[72:75], v[6:7], off offset:3072
	s_waitcnt vmcnt(0)
.LBB0_518:
	global_load_dwordx4 v[18:21], v[10:11], off offset:-3072
	global_load_dwordx4 v[22:25], v[10:11], off offset:-2048
	global_load_dwordx4 v[26:29], v[10:11], off offset:-1024
	global_load_dwordx4 v[2:5], v[10:11], off
	s_mov_b32 s1, 0xf8800000
	v_add_co_u32_e32 v34, vcc, s1, v8
	s_add_i32 s10, s10, s0
	s_nop 0
	v_addc_co_u32_e32 v35, vcc, -1, v9, vcc
	v_lshl_add_u64 v[10:11], v[10:11], 0, s[4:5]
	s_cmpk_lt_i32 s10, 0x4000
	s_waitcnt vmcnt(0)
	v_cvt_pk_bf16_f32 v30, v18, v19
	v_cvt_pk_bf16_f32 v31, v20, v21
	v_cvt_pk_bf16_f32 v32, v22, v23
	v_cvt_pk_bf16_f32 v33, v24, v25
	v_pk_mul_f32 v[40:41], v[20:21], v[20:21]
	v_pk_mul_f32 v[42:43], v[18:19], v[18:19]
	v_pk_mul_f32 v[44:45], v[24:25], v[24:25]
	v_pk_mul_f32 v[46:47], v[22:23], v[22:23]
	v_cvt_pk_bf16_f32 v36, v26, v27
	v_cvt_pk_bf16_f32 v37, v28, v29
	v_cvt_pk_bf16_f32 v38, v2, v3
	v_cvt_pk_bf16_f32 v39, v4, v5
	global_store_dwordx2 v[8:9], v[30:31], off offset:-1536
	global_store_dwordx2 v[8:9], v[32:33], off offset:-1024
	global_store_dwordx2 v[8:9], v[36:37], off offset:-512
	global_store_dwordx2 v[8:9], v[38:39], off
	v_pk_mov_b32 v[30:31], v[42:43], v[40:41] op_sel:[1,0]
	v_mov_b32_e32 v43, v41
	v_pk_mov_b32 v[32:33], v[46:47], v[44:45] op_sel:[1,0]
	v_mov_b32_e32 v47, v45
	v_pk_add_f32 v[40:41], v[30:31], v[42:43]
	v_pk_add_f32 v[42:43], v[32:33], v[46:47]
	v_mul_f32_e32 v49, v2, v2
	v_mul_f32_e32 v0, v27, v27
	v_mul_f32_e32 v48, v29, v29
	v_mul_f32_e32 v50, v3, v3
	v_mul_f32_e32 v51, v4, v4
	v_mul_f32_e32 v52, v5, v5
	v_pk_fma_f32 v[36:37], v[26:27], v[26:27], v[0:1] op_sel_hi:[1,1,0]
	v_pk_fma_f32 v[38:39], v[28:29], v[28:29], v[48:49] op_sel_hi:[1,1,0]
	v_pk_add_f32 v[40:41], v[40:41], v[40:41] op_sel:[0,1] op_sel_hi:[1,0]
	v_pk_add_f32 v[42:43], v[42:43], v[42:43] op_sel:[0,1] op_sel_hi:[1,0]
	v_mov_b32_e32 v37, v51
	v_mov_b32_e32 v39, v52
	v_mov_b32_e32 v41, v49
	v_mov_b32_e32 v43, v50
	v_pk_add_f32 v[36:37], v[36:37], v[38:39]
	v_pk_add_f32 v[38:39], v[40:41], v[42:43]
	v_lshl_add_u64 v[8:9], v[8:9], 0, s[2:3]
	v_pk_add_f32 v[36:37], v[38:39], v[36:37]
	v_pk_mul_f32 v[20:21], v[20:21], v[62:63]
	v_add_f32_e32 v0, v36, v37
	ds_bpermute_b32 v36, v12, v0
	v_pk_mul_f32 v[18:19], v[18:19], v[60:61]
	s_waitcnt lgkmcnt(0)
	v_add_f32_e32 v0, v0, v36
	ds_bpermute_b32 v36, v13, v0
	s_waitcnt lgkmcnt(0)
	v_add_f32_e32 v0, v0, v36
	ds_bpermute_b32 v36, v14, v0
	s_waitcnt lgkmcnt(0)
	v_add_f32_e32 v0, v0, v36
	ds_bpermute_b32 v36, v15, v0
	s_waitcnt lgkmcnt(0)
	v_add_f32_e32 v0, v0, v36
	ds_bpermute_b32 v36, v16, v0
	s_waitcnt lgkmcnt(0)
	v_add_f32_e32 v0, v0, v36
	ds_bpermute_b32 v36, v17, v0
	s_waitcnt lgkmcnt(0)
	v_add_f32_e32 v0, v0, v36
	v_fmamk_f32 v0, v0, 0x3a800000, v230
	v_mul_f32_e32 v36, 0x4f800000, v0
	v_cmp_gt_f32_e32 vcc, s80, v0
	s_nop 1
	v_cndmask_b32_e32 v0, v0, v36, vcc
	v_sqrt_f32_e32 v36, v0
	s_nop 0
	v_add_u32_e32 v37, -1, v36
	v_add_u32_e32 v38, 1, v36
	v_fma_f32 v39, -v37, v36, v0
	v_fma_f32 v40, -v38, v36, v0
	v_cmp_ge_f32_e64 s[6:7], 0, v39
	s_nop 1
	v_cndmask_b32_e64 v36, v36, v37, s[6:7]
	v_cmp_lt_f32_e64 s[6:7], 0, v40
	s_nop 1
	v_cndmask_b32_e64 v36, v36, v38, s[6:7]
	v_mul_f32_e32 v37, 0x37800000, v36
	v_cndmask_b32_e32 v36, v36, v37, vcc
	v_cmp_class_f32_e32 vcc, v0, v231
	s_nop 1
	v_cndmask_b32_e32 v0, v36, v0, vcc
	v_div_scale_f32 v36, s[6:7], v0, v0, 1.0
	v_rcp_f32_e32 v38, v36
	v_div_scale_f32 v37, vcc, 1.0, v0, 1.0
	v_fma_f32 v39, -v36, v38, 1.0
	v_fmac_f32_e32 v38, v39, v38
	v_mul_f32_e32 v39, v37, v38
	v_fma_f32 v40, -v36, v39, v37
	v_fmac_f32_e32 v39, v40, v38
	v_fma_f32 v36, -v36, v39, v37
	v_div_fmas_f32 v36, v36, v38, v39
	v_div_fixup_f32 v0, v36, v0, 1.0
	v_pk_mul_f32 v[20:21], v[20:21], v[0:1] op_sel_hi:[1,0]
	v_pk_mul_f32 v[18:19], v[18:19], v[0:1] op_sel_hi:[1,0]
	s_nop 0
	v_cvt_pk_bf16_f32 v18, v18, v19
	v_cvt_pk_bf16_f32 v19, v20, v21
	global_store_dwordx2 v[34:35], v[18:19], off offset:-1536
	v_pk_mul_f32 v[20:21], v[24:25], v[66:67]
	v_pk_mul_f32 v[18:19], v[22:23], v[64:65]
	v_pk_mul_f32 v[20:21], v[20:21], v[0:1] op_sel_hi:[1,0]
	v_pk_mul_f32 v[18:19], v[18:19], v[0:1] op_sel_hi:[1,0]
	s_nop 0
	v_cvt_pk_bf16_f32 v18, v18, v19
	v_cvt_pk_bf16_f32 v19, v20, v21
	global_store_dwordx2 v[34:35], v[18:19], off offset:-1024
	v_pk_mul_f32 v[20:21], v[28:29], v[70:71]
	v_pk_mul_f32 v[18:19], v[26:27], v[68:69]
	v_pk_mul_f32 v[20:21], v[20:21], v[0:1] op_sel_hi:[1,0]
	v_pk_mul_f32 v[18:19], v[18:19], v[0:1] op_sel_hi:[1,0]
	s_nop 0
	v_cvt_pk_bf16_f32 v18, v18, v19
	v_cvt_pk_bf16_f32 v19, v20, v21
	global_store_dwordx2 v[34:35], v[18:19], off offset:-512
	v_pk_mul_f32 v[4:5], v[4:5], v[74:75]
	v_pk_mul_f32 v[2:3], v[2:3], v[72:73]
	v_pk_mul_f32 v[4:5], v[0:1], v[4:5] op_sel_hi:[0,1]
	v_pk_mul_f32 v[2:3], v[0:1], v[2:3] op_sel_hi:[0,1]
	v_cvt_pk_bf16_f32 v2, v2, v3
	v_cvt_pk_bf16_f32 v3, v4, v5
	global_store_dwordx2 v[34:35], v[2:3], off
	s_cbranch_scc1 .LBB0_518
	s_branch .LBB0_7
